# v013 plus one static s_setprio 1 for waves 0-3 over each attention kv loop
# speedup vs baseline: 1.0053x; 1.0015x over previous
.Lh1_first:
	s_cmp_gt_u32 s96, 3
	s_cbranch_scc1 .Lprio_skip
	s_setprio 1
